# LN adaLN-modulation vectors fetched in one batch per row; adaLN GEMV keeps 32 weight rows in flight per iteration
# baseline (speedup 1.0000x reference)
; __device__ __forceinline__ void row_stats(const f32x4 (&v)[8], float& mean, float& rstd) {
;     float s = 0.f;
; #pragma unroll
;     for (int i = 0; i < 8; ++i) s += v[i][0] + v[i][1] + v[i][2] + v[i][3];
;     mean = wsum(s) * (1.f / 2048.f);
;     float q = 0.f;
; #pragma unroll
;     for (int i = 0; i < 8; ++i) { const f32x4 d = v[i] - mean; q += d[0] * d[0] + d[1] * d[1] + d[2] * d[2] + d[3] * d[3]; }
;     rstd = rsqrtf(wsum(q) * (1.f / 2048.f) + LN_EPS);
; __device__ void phase_ln(const Params& p, int l) {
;     ...
;         row_stats(v, mean, rstd);
;         const float* md = p.MOD + (size_t)(l * 3 + (isctx ? 2 : b)) * 6144;
;         u16* ur = p.U + (size_t)row * 2048;
; #pragma unroll
;         for (int i = 0; i < 8; ++i) { const f32x4 sh = *(const f32x4*)(md + i * 256 + lane * 4), sc = *(const f32x4*)(md + 2048 + i * 256 + lane * 4);
.LBB0_352:
	s_andn2_b64 vcc, exec, s[22:23]
	s_cbranch_vccnz .LBB0_344
	s_waitcnt vmcnt(0)
	v_add_f32_e32 v35, v28, v29
	v_add_f32_e32 v35, v30, v35
	v_add_f32_e32 v61, v24, v25
	v_add_f32_e32 v35, v31, v35
	v_add_f32_e32 v61, v26, v61
	v_add_f32_e32 v35, 0, v35
	v_add_f32_e32 v61, v27, v61
	v_add_f32_e32 v35, v61, v35
	v_add_f32_e32 v61, v20, v21
	v_add_f32_e32 v61, v22, v61
	v_add_f32_e32 v61, v23, v61
	v_add_f32_e32 v35, v61, v35
	v_add_f32_e32 v61, v16, v17
	v_mov_b32_e32 v62, v8
	v_mov_b32_e32 v63, v12
	v_mov_b32_e32 v64, v9
	v_mov_b32_e32 v65, v13
	v_add_f32_e32 v61, v18, v61
	v_pk_add_f32 v[62:63], v[62:63], v[64:65]
	v_mov_b32_e32 v64, v10
	v_mov_b32_e32 v65, v14
	v_add_f32_e32 v61, v19, v61
	v_pk_add_f32 v[62:63], v[64:65], v[62:63]
	v_mov_b32_e32 v64, v11
	v_mov_b32_e32 v65, v15
	v_add_f32_e32 v35, v61, v35
	v_pk_add_f32 v[62:63], v[64:65], v[62:63]
	v_mov_b32_e32 v64, v1
	v_add_f32_e32 v35, v63, v35
	v_add_f32_e32 v35, v62, v35
	v_mov_b32_e32 v62, v0
	v_mov_b32_e32 v63, v4
	v_mov_b32_e32 v65, v5
	v_pk_add_f32 v[62:63], v[62:63], v[64:65]
	v_mov_b32_e32 v64, v2
	v_mov_b32_e32 v65, v6
	v_pk_add_f32 v[62:63], v[64:65], v[62:63]
	v_mov_b32_e32 v64, v3
	v_mov_b32_e32 v65, v7
	v_pk_add_f32 v[62:63], v[64:65], v[62:63]
	v_cmp_lt_i32_e32 vcc, v211, v210
	v_add_f32_e32 v35, v63, v35
	v_add_f32_e32 v35, v62, v35
	v_cndmask_b32_e32 v61, v208, v211, vcc
	v_lshlrev_b32_e32 v82, 2, v61
	ds_bpermute_b32 v61, v82, v35
	v_cmp_lt_i32_e32 vcc, v212, v210
	v_lshrrev_b32_e32 v60, 13, v60
	v_cndmask_b32_e64 v60, v60, 2, s[6:7]
	s_waitcnt lgkmcnt(0)
	v_add_f32_e32 v35, v35, v61
	v_cndmask_b32_e32 v61, v208, v212, vcc
	v_lshlrev_b32_e32 v83, 2, v61
	ds_bpermute_b32 v61, v83, v35
	v_cmp_lt_i32_e32 vcc, v213, v210
	s_waitcnt lgkmcnt(0)
	v_add_f32_e32 v35, v35, v61
	v_cndmask_b32_e32 v61, v208, v213, vcc
	v_lshlrev_b32_e32 v84, 2, v61
	ds_bpermute_b32 v61, v84, v35
	v_cmp_lt_i32_e32 vcc, v214, v210
	s_waitcnt lgkmcnt(0)
	v_add_f32_e32 v35, v35, v61
	v_cndmask_b32_e32 v61, v208, v214, vcc
	v_lshlrev_b32_e32 v85, 2, v61
	ds_bpermute_b32 v61, v85, v35
	v_cmp_lt_i32_e32 vcc, v215, v210
	s_waitcnt lgkmcnt(0)
	v_add_f32_e32 v35, v35, v61
	v_cndmask_b32_e32 v61, v208, v215, vcc
	v_lshlrev_b32_e32 v86, 2, v61
	ds_bpermute_b32 v61, v86, v35
	v_cmp_lt_i32_e32 vcc, v216, v210
	s_waitcnt lgkmcnt(0)
	v_add_f32_e32 v35, v35, v61
	v_cndmask_b32_e32 v61, v208, v216, vcc
	v_lshlrev_b32_e32 v87, 2, v61
	ds_bpermute_b32 v61, v87, v35
	s_waitcnt lgkmcnt(0)
	v_add_f32_e32 v35, v35, v61
	v_fmac_f32_e32 v29, 0xba000000, v35
	v_fmac_f32_e32 v25, 0xba000000, v35
	v_fmamk_f32 v28, v35, 0xba000000, v28
	v_mul_f32_e32 v61, v29, v29
	v_fmamk_f32 v68, v35, 0xba000000, v26
	v_fmamk_f32 v24, v35, 0xba000000, v24
	v_mul_f32_e32 v26, v25, v25
	v_fmac_f32_e32 v21, 0xba000000, v35
	v_fmamk_f32 v30, v35, 0xba000000, v30
	v_fmac_f32_e32 v61, v28, v28
	v_fmac_f32_e32 v26, v24, v24
	v_fmamk_f32 v70, v35, 0xba000000, v22
	v_fmamk_f32 v20, v35, 0xba000000, v20
	v_mul_f32_e32 v22, v21, v21
	v_fmac_f32_e32 v17, 0xba000000, v35
	v_fmamk_f32 v31, v35, 0xba000000, v31
	v_fmac_f32_e32 v61, v30, v30
	v_fmamk_f32 v69, v35, 0xba000000, v27
	v_fmac_f32_e32 v26, v68, v68
	v_fmac_f32_e32 v22, v20, v20
	v_fmamk_f32 v72, v35, 0xba000000, v18
	v_fmamk_f32 v16, v35, 0xba000000, v16
	v_mul_f32_e32 v18, v17, v17
	v_fmac_f32_e32 v61, v31, v31
	v_fmac_f32_e32 v26, v69, v69
	v_fmamk_f32 v71, v35, 0xba000000, v23
	v_fmac_f32_e32 v22, v70, v70
	v_fmac_f32_e32 v18, v16, v16
	v_add_f32_e32 v26, v61, v26
	v_fmac_f32_e32 v22, v71, v71
	v_fmamk_f32 v73, v35, 0xba000000, v19
	v_fmac_f32_e32 v18, v72, v72
	v_add_f32_e32 v22, v22, v26
	v_fmac_f32_e32 v18, v73, v73
	v_fmamk_f32 v13, v35, 0xba000000, v13
	v_fmamk_f32 v9, v35, 0xba000000, v9
	v_add_f32_e32 v26, v18, v22
	v_fmac_f32_e32 v12, 0xba000000, v35
	v_fmac_f32_e32 v8, 0xba000000, v35
	v_mov_b32_e32 v22, v9
	v_mov_b32_e32 v23, v13
	v_mov_b32_e32 v18, v8
	v_mov_b32_e32 v19, v12
	v_pk_mul_f32 v[22:23], v[22:23], v[22:23]
	v_add_u32_e32 v27, s44, v60
	v_pk_fma_f32 v[18:19], v[18:19], v[18:19], v[22:23]
	v_mov_b64_e32 v[22:23], s[16:17]
	v_mad_i64_i32 v[22:23], s[6:7], v27, s65, v[22:23]
	v_lshl_add_u64 v[74:75], v[22:23], 0, v[148:149]
	s_movk_i32 s6, 0x3000
	v_add_co_u32_e32 v76, vcc, s6, v74
	v_fmamk_f32 v14, v35, 0xba000000, v14
	s_nop 0
	v_addc_co_u32_e32 v77, vcc, 0, v75, vcc
	global_load_dwordx4 v[60:63], v[74:75], off
	global_load_dwordx4 v[64:67], v[76:77], off offset:-4096
	v_fmamk_f32 v10, v35, 0xba000000, v10
	v_fmamk_f32 v5, v35, 0xba000000, v5
	v_fmamk_f32 v1, v35, 0xba000000, v1
	v_fmamk_f32 v15, v35, 0xba000000, v15
	v_fmamk_f32 v11, v35, 0xba000000, v11
	v_mov_b32_e32 v22, v10
	v_mov_b32_e32 v23, v14
	v_fmamk_f32 v79, v35, 0xba000000, v7
	v_fmamk_f32 v78, v35, 0xba000000, v6
	v_fmac_f32_e32 v4, 0xba000000, v35
	v_fmac_f32_e32 v0, 0xba000000, v35
	v_mov_b32_e32 v6, v1
	v_mov_b32_e32 v7, v5
	v_pk_fma_f32 v[18:19], v[22:23], v[22:23], v[18:19]
	v_mov_b32_e32 v22, v11
	v_mov_b32_e32 v23, v15
	v_fmamk_f32 v81, v35, 0xba000000, v3
	v_fmamk_f32 v80, v35, 0xba000000, v2
	v_mov_b32_e32 v2, v0
	v_mov_b32_e32 v3, v4
	v_pk_mul_f32 v[6:7], v[6:7], v[6:7]
	v_pk_fma_f32 v[18:19], v[22:23], v[22:23], v[18:19]
	v_pk_fma_f32 v[2:3], v[2:3], v[2:3], v[6:7]
	v_mov_b32_e32 v6, v80
	v_mov_b32_e32 v7, v78
	v_add_f32_e32 v19, v19, v26
	v_pk_fma_f32 v[2:3], v[6:7], v[6:7], v[2:3]
	v_mov_b32_e32 v6, v81
	v_mov_b32_e32 v7, v79
	v_add_f32_e32 v18, v18, v19
	v_pk_fma_f32 v[2:3], v[6:7], v[6:7], v[2:3]
	s_mov_b64 s[6:7], 0x2000
	v_add_f32_e32 v3, v3, v18
	v_add_f32_e32 v2, v2, v3
	ds_bpermute_b32 v3, v82, v2
	s_waitcnt lgkmcnt(0)
	v_add_f32_e32 v2, v2, v3
	ds_bpermute_b32 v3, v83, v2
	s_waitcnt lgkmcnt(0)
; __device__ __forceinline__ unsigned pk2(float lo, float hi) { const f32x2_t v = {lo, hi}; return __builtin_bit_cast(unsigned, __builtin_convertvector(v, bf16x2_t)); }
; __device__ void phase_ln(const Params& p, int l) {
;     ...
;         const float* md = p.MOD + (size_t)(l * 3 + (isctx ? 2 : b)) * 6144;
;         u16* ur = p.U + (size_t)row * 2048;
; #pragma unroll
;         for (int i = 0; i < 8; ++i) { const f32x4 sh = *(const f32x4*)(md + i * 256 + lane * 4), sc = *(const f32x4*)(md + 2048 + i * 256 + lane * 4);
;             const f32x4 o = (v[i] - mean) * rstd * (sc + 1.f) + sh;
;             u32x2 w; w.x = pk2(o[0], o[1]); w.y = pk2(o[2], o[3]);
;             *(u32x2*)(ur + i * 256 + lane * 4) = w; }
	v_add_f32_e32 v2, v2, v3
	ds_bpermute_b32 v3, v84, v2
	s_waitcnt lgkmcnt(0)
	v_add_f32_e32 v2, v2, v3
	ds_bpermute_b32 v3, v85, v2
	s_waitcnt lgkmcnt(0)
	v_add_f32_e32 v2, v2, v3
	ds_bpermute_b32 v3, v86, v2
	s_waitcnt lgkmcnt(0)
	v_add_f32_e32 v2, v2, v3
	ds_bpermute_b32 v3, v87, v2
	s_waitcnt lgkmcnt(0)
	v_add_f32_e32 v2, v2, v3
	v_fmamk_f32 v2, v2, 0x3a000000, v207
	v_mul_f32_e32 v3, 0x4b800000, v2
	v_cmp_gt_f32_e32 vcc, s41, v2
	s_waitcnt vmcnt(0)
	v_pk_add_f32 v[22:23], v[66:67], 1.0 op_sel_hi:[1,0]
	v_cndmask_b32_e32 v2, v2, v3, vcc
	v_rsq_f32_e32 v2, v2
	v_pk_add_f32 v[26:27], v[64:65], 1.0 op_sel_hi:[1,0]
	v_mul_f32_e32 v3, 0x45800000, v2
	v_cndmask_b32_e32 v82, v2, v3, vcc
	v_pk_mul_f32 v[6:7], v[28:29], v[82:83] op_sel_hi:[1,0]
	v_pk_mul_f32 v[18:19], v[30:31], v[82:83] op_sel_hi:[1,0]
	v_pk_fma_f32 v[6:7], v[26:27], v[6:7], v[60:61]
	v_pk_fma_f32 v[18:19], v[22:23], v[18:19], v[62:63]
	v_cvt_pk_bf16_f32 v6, v6, v7
	v_cvt_pk_bf16_f32 v7, v18, v19
	v_lshl_add_u64 v[2:3], v[74:75], 0, s[6:7]
	global_store_dwordx2 v[56:57], v[6:7], off
	v_add_co_u32_e32 v232, vcc, s69, v74
	global_load_dwordx4 v[158:161], v[2:3], off offset:1024
	global_load_dwordx4 v[162:165], v[74:75], off offset:1024
	v_addc_co_u32_e32 v233, vcc, 0, v75, vcc
	global_load_dwordx4 v[166:169], v[2:3], off offset:2048
	global_load_dwordx4 v[170:173], v[74:75], off offset:2048
	global_load_dwordx4 v[174:177], v[2:3], off offset:3072
	global_load_dwordx4 v[178:181], v[74:75], off offset:3072
	global_load_dwordx4 v[182:185], v[76:77], off
	global_load_dwordx4 v[186:189], v[232:233], off
	global_load_dwordx4 v[190:193], v[76:77], off offset:1024
	global_load_dwordx4 v[194:197], v[232:233], off offset:1024
	global_load_dwordx4 v[198:201], v[76:77], off offset:2048
	global_load_dwordx4 v[202:205], v[232:233], off offset:2048
	global_load_dwordx4 v[224:227], v[76:77], off offset:3072
	global_load_dwordx4 v[228:231], v[232:233], off offset:3072
	v_pk_mul_f32 v[6:7], v[24:25], v[82:83] op_sel_hi:[1,0]
	v_pk_mul_f32 v[18:19], v[68:69], v[82:83] op_sel_hi:[1,0]
	v_pk_mul_f32 v[0:1], v[0:1], v[82:83] op_sel_hi:[1,0]
	s_waitcnt vmcnt(12)
	v_mov_b64_e32 v[26:27], v[158:159]
	v_mov_b64_e32 v[28:29], v[160:161]
	v_mov_b64_e32 v[60:61], v[162:163]
	v_mov_b64_e32 v[62:63], v[164:165]
	v_pk_add_f32 v[22:23], v[28:29], 1.0 op_sel_hi:[1,0]
	v_pk_add_f32 v[24:25], v[26:27], 1.0 op_sel_hi:[1,0]
	v_pk_fma_f32 v[18:19], v[22:23], v[18:19], v[62:63]
	v_pk_fma_f32 v[6:7], v[24:25], v[6:7], v[60:61]
	s_nop 0
	v_cvt_pk_bf16_f32 v6, v6, v7
	v_cvt_pk_bf16_f32 v7, v18, v19
	global_store_dwordx2 v[56:57], v[6:7], off offset:512
	v_pk_mul_f32 v[6:7], v[20:21], v[82:83] op_sel_hi:[1,0]
	v_pk_mul_f32 v[18:19], v[70:71], v[82:83] op_sel_hi:[1,0]
	s_waitcnt vmcnt(11)
	v_mov_b64_e32 v[22:23], v[166:167]
	v_mov_b64_e32 v[24:25], v[168:169]
	v_mov_b64_e32 v[26:27], v[170:171]
	v_mov_b64_e32 v[28:29], v[172:173]
	v_pk_add_f32 v[20:21], v[24:25], 1.0 op_sel_hi:[1,0]
	v_pk_add_f32 v[22:23], v[22:23], 1.0 op_sel_hi:[1,0]
	v_pk_fma_f32 v[18:19], v[20:21], v[18:19], v[28:29]
	v_pk_fma_f32 v[6:7], v[22:23], v[6:7], v[26:27]
	s_nop 0
	v_cvt_pk_bf16_f32 v6, v6, v7
	v_cvt_pk_bf16_f32 v7, v18, v19
	global_store_dwordx2 v[56:57], v[6:7], off offset:1024
	v_pk_mul_f32 v[2:3], v[16:17], v[82:83] op_sel_hi:[1,0]
	v_pk_mul_f32 v[6:7], v[72:73], v[82:83] op_sel_hi:[1,0]
	s_waitcnt vmcnt(10)
	v_mov_b64_e32 v[18:19], v[174:175]
	v_mov_b64_e32 v[20:21], v[176:177]
	v_mov_b64_e32 v[22:23], v[178:179]
	v_mov_b64_e32 v[24:25], v[180:181]
	v_pk_add_f32 v[16:17], v[20:21], 1.0 op_sel_hi:[1,0]
	v_pk_add_f32 v[18:19], v[18:19], 1.0 op_sel_hi:[1,0]
	v_pk_fma_f32 v[6:7], v[16:17], v[6:7], v[24:25]
	v_pk_fma_f32 v[2:3], v[18:19], v[2:3], v[22:23]
	v_add_co_u32_e32 v24, vcc, s69, v74
	v_cvt_pk_bf16_f32 v2, v2, v3
	v_cvt_pk_bf16_f32 v3, v6, v7
	global_store_dwordx2 v[56:57], v[2:3], off offset:1536
	v_addc_co_u32_e32 v25, vcc, 0, v75, vcc
	v_pk_mul_f32 v[2:3], v[12:13], v[82:83] op_sel_hi:[1,0]
	v_pk_mul_f32 v[6:7], v[14:15], v[82:83] op_sel_hi:[1,0]
	s_waitcnt vmcnt(9)
	v_mov_b64_e32 v[16:17], v[182:183]
	v_mov_b64_e32 v[18:19], v[184:185]
	v_mov_b64_e32 v[20:21], v[186:187]
	v_mov_b64_e32 v[22:23], v[188:189]
	v_pk_add_f32 v[12:13], v[18:19], 1.0 op_sel_hi:[1,0]
	v_pk_add_f32 v[14:15], v[16:17], 1.0 op_sel_hi:[1,0]
	v_pk_fma_f32 v[6:7], v[12:13], v[6:7], v[22:23]
	v_pk_fma_f32 v[2:3], v[14:15], v[2:3], v[20:21]
	s_nop 0
	v_cvt_pk_bf16_f32 v2, v2, v3
	v_cvt_pk_bf16_f32 v3, v6, v7
	global_store_dwordx2 v[56:57], v[2:3], off offset:2048
	v_pk_mul_f32 v[2:3], v[8:9], v[82:83] op_sel_hi:[1,0]
	v_pk_mul_f32 v[6:7], v[10:11], v[82:83] op_sel_hi:[1,0]
	s_waitcnt vmcnt(8)
	v_mov_b64_e32 v[12:13], v[190:191]
	v_mov_b64_e32 v[14:15], v[192:193]
	v_mov_b64_e32 v[16:17], v[194:195]
	v_mov_b64_e32 v[18:19], v[196:197]
	v_pk_add_f32 v[8:9], v[14:15], 1.0 op_sel_hi:[1,0]
	v_pk_add_f32 v[10:11], v[12:13], 1.0 op_sel_hi:[1,0]
	v_pk_fma_f32 v[6:7], v[8:9], v[6:7], v[18:19]
	v_pk_fma_f32 v[2:3], v[10:11], v[2:3], v[16:17]
	s_nop 0
	v_cvt_pk_bf16_f32 v2, v2, v3
	v_cvt_pk_bf16_f32 v3, v6, v7
	global_store_dwordx2 v[56:57], v[2:3], off offset:2560
	v_pk_mul_f32 v[2:3], v[4:5], v[82:83] op_sel_hi:[1,0]
	v_pk_mul_f32 v[4:5], v[78:79], v[82:83] op_sel_hi:[1,0]
	s_waitcnt vmcnt(7)
	v_mov_b64_e32 v[6:7], v[198:199]
	v_mov_b64_e32 v[8:9], v[200:201]
	v_mov_b64_e32 v[10:11], v[202:203]
	v_mov_b64_e32 v[12:13], v[204:205]
	v_pk_add_f32 v[8:9], v[8:9], 1.0 op_sel_hi:[1,0]
	v_pk_add_f32 v[6:7], v[6:7], 1.0 op_sel_hi:[1,0]
	v_pk_fma_f32 v[4:5], v[8:9], v[4:5], v[12:13]
	v_pk_fma_f32 v[2:3], v[6:7], v[2:3], v[10:11]
	v_pk_mul_f32 v[10:11], v[80:81], v[82:83] op_sel_hi:[1,0]
	v_cvt_pk_bf16_f32 v2, v2, v3
	v_cvt_pk_bf16_f32 v3, v4, v5
	global_store_dwordx2 v[56:57], v[2:3], off offset:3072
	s_waitcnt vmcnt(6)
	v_mov_b64_e32 v[2:3], v[224:225]
	v_mov_b64_e32 v[4:5], v[226:227]
	v_mov_b64_e32 v[6:7], v[228:229]
	v_mov_b64_e32 v[8:9], v[230:231]
	v_pk_add_f32 v[4:5], v[4:5], 1.0 op_sel_hi:[1,0]
	v_pk_add_f32 v[2:3], v[2:3], 1.0 op_sel_hi:[1,0]
	v_pk_fma_f32 v[4:5], v[4:5], v[10:11], v[8:9]
	v_pk_fma_f32 v[0:1], v[2:3], v[0:1], v[6:7]
	s_nop 0
	v_cvt_pk_bf16_f32 v0, v0, v1
	v_cvt_pk_bf16_f32 v1, v4, v5
	global_store_dwordx2 v[56:57], v[0:1], off offset:3584
	s_branch .LBB0_344

; __device__ void phase_a(const Params& p, unsigned char* lds) {
;     ...
;         const int l = t / 96, cb = t % 96; const int col = cb * 64 + (tid & 63); const int kg = tid >> 6;
;         const float* w = p.w_ada + (size_t)l * 2048 * 6144 + col;
;         float a0 = 0.f, a1 = 0.f, a2 = 0.f;
; #pragma unroll 8
;         for (int k = kg * 256; k < kg * 256 + 256; ++k) { const float wv = w[(size_t)k * 6144]; a0 += sf[k] * wv; a1 += sf[2048 + k] * wv; a2 += sf[4096 + k] * wv; }
.LBB0_448:
	v_lshl_add_u64 v[16:17], v[10:11], 0, s[16:17]
	s_mov_b64 s[6:7], 0x6000
	s_add_u32 s16, s16, 0xc0000
	s_addc_u32 s17, s17, 0
	global_load_dword v64, v[16:17], off
	v_lshl_add_u64 v[18:19], v[16:17], 0, s[6:7]
	global_load_dword v66, v[18:19], off
	v_lshl_add_u64 v[16:17], v[18:19], 0, s[6:7]
	global_load_dword v68, v[16:17], off
	v_lshl_add_u64 v[18:19], v[16:17], 0, s[6:7]
	global_load_dword v70, v[18:19], off
	v_lshl_add_u64 v[16:17], v[18:19], 0, s[6:7]
	global_load_dword v72, v[16:17], off
	v_lshl_add_u64 v[18:19], v[16:17], 0, s[6:7]
	global_load_dword v74, v[18:19], off
	v_lshl_add_u64 v[16:17], v[18:19], 0, s[6:7]
	global_load_dword v76, v[16:17], off
	v_lshl_add_u64 v[18:19], v[16:17], 0, s[6:7]
	global_load_dword v78, v[18:19], off
	v_lshl_add_u64 v[16:17], v[18:19], 0, s[6:7]
	global_load_dword v80, v[16:17], off
	v_lshl_add_u64 v[18:19], v[16:17], 0, s[6:7]
	global_load_dword v82, v[18:19], off
	v_lshl_add_u64 v[16:17], v[18:19], 0, s[6:7]
	global_load_dword v84, v[16:17], off
	v_lshl_add_u64 v[18:19], v[16:17], 0, s[6:7]
	global_load_dword v86, v[18:19], off
	v_lshl_add_u64 v[16:17], v[18:19], 0, s[6:7]
	global_load_dword v88, v[16:17], off
	v_lshl_add_u64 v[18:19], v[16:17], 0, s[6:7]
	global_load_dword v90, v[18:19], off
	v_lshl_add_u64 v[16:17], v[18:19], 0, s[6:7]
	global_load_dword v92, v[16:17], off
	v_lshl_add_u64 v[18:19], v[16:17], 0, s[6:7]
	global_load_dword v94, v[18:19], off
	v_lshl_add_u64 v[16:17], v[18:19], 0, s[6:7]
	global_load_dword v96, v[16:17], off
	v_lshl_add_u64 v[18:19], v[16:17], 0, s[6:7]
	global_load_dword v98, v[18:19], off
	v_lshl_add_u64 v[16:17], v[18:19], 0, s[6:7]
	global_load_dword v100, v[16:17], off
	v_lshl_add_u64 v[18:19], v[16:17], 0, s[6:7]
	global_load_dword v102, v[18:19], off
	v_lshl_add_u64 v[16:17], v[18:19], 0, s[6:7]
	global_load_dword v104, v[16:17], off
	v_lshl_add_u64 v[18:19], v[16:17], 0, s[6:7]
	global_load_dword v106, v[18:19], off
	v_lshl_add_u64 v[16:17], v[18:19], 0, s[6:7]
	global_load_dword v108, v[16:17], off
	v_lshl_add_u64 v[18:19], v[16:17], 0, s[6:7]
	global_load_dword v110, v[18:19], off
	v_lshl_add_u64 v[16:17], v[18:19], 0, s[6:7]
	global_load_dword v112, v[16:17], off
	v_lshl_add_u64 v[18:19], v[16:17], 0, s[6:7]
	global_load_dword v114, v[18:19], off
	v_lshl_add_u64 v[16:17], v[18:19], 0, s[6:7]
	global_load_dword v116, v[16:17], off
	v_lshl_add_u64 v[18:19], v[16:17], 0, s[6:7]
	global_load_dword v118, v[18:19], off
	v_lshl_add_u64 v[16:17], v[18:19], 0, s[6:7]
	global_load_dword v120, v[16:17], off
	v_lshl_add_u64 v[18:19], v[16:17], 0, s[6:7]
	global_load_dword v122, v[18:19], off
	v_lshl_add_u64 v[16:17], v[18:19], 0, s[6:7]
	global_load_dword v124, v[16:17], off
	v_lshl_add_u64 v[18:19], v[16:17], 0, s[6:7]
	global_load_dword v126, v[18:19], off
	ds_read_b128 v[16:19], v15
	ds_read_b128 v[20:23], v15 offset:16
	ds_read_b128 v[24:27], v15 offset:8192
	ds_read_b128 v[28:31], v15 offset:8208
	ds_read_b128 v[32:35], v15 offset:16384
	ds_read_b128 v[36:39], v15 offset:16400
	s_waitcnt lgkmcnt(0)
	v_mov_b32_e32 v56, v16
	v_mov_b32_e32 v57, v24
	v_mov_b32_e32 v24, v17
	v_mov_b32_e32 v16, v18
	v_mov_b32_e32 v17, v26
	v_mov_b32_e32 v26, v19
	v_mov_b32_e32 v18, v20
	v_mov_b32_e32 v19, v28
	v_mov_b32_e32 v28, v21
	v_mov_b32_e32 v20, v22
	v_mov_b32_e32 v21, v30
	v_mov_b32_e32 v30, v23
	s_waitcnt vmcnt(31)
	v_pk_fma_f32 v[12:13], v[64:65], v[56:57], v[12:13] op_sel_hi:[0,1,1]
	v_fmac_f32_e32 v14, v64, v32
	s_waitcnt vmcnt(30)
	v_pk_fma_f32 v[12:13], v[66:67], v[24:25], v[12:13] op_sel_hi:[0,1,1]
	v_fmac_f32_e32 v14, v66, v33
	s_waitcnt vmcnt(29)
	v_pk_fma_f32 v[12:13], v[68:69], v[16:17], v[12:13] op_sel_hi:[0,1,1]
	v_fmac_f32_e32 v14, v68, v34
	s_waitcnt vmcnt(28)
	v_pk_fma_f32 v[12:13], v[70:71], v[26:27], v[12:13] op_sel_hi:[0,1,1]
	v_fmac_f32_e32 v14, v70, v35
	s_waitcnt vmcnt(27)
	v_pk_fma_f32 v[12:13], v[72:73], v[18:19], v[12:13] op_sel_hi:[0,1,1]
	v_fmac_f32_e32 v14, v72, v36
	s_waitcnt vmcnt(26)
	v_pk_fma_f32 v[12:13], v[74:75], v[28:29], v[12:13] op_sel_hi:[0,1,1]
	v_fmac_f32_e32 v14, v74, v37
	s_waitcnt vmcnt(25)
	v_pk_fma_f32 v[12:13], v[76:77], v[20:21], v[12:13] op_sel_hi:[0,1,1]
	v_fmac_f32_e32 v14, v76, v38
	s_waitcnt vmcnt(24)
	v_pk_fma_f32 v[12:13], v[78:79], v[30:31], v[12:13] op_sel_hi:[0,1,1]
	v_fmac_f32_e32 v14, v78, v39
	ds_read_b128 v[16:19], v15 offset:32
	ds_read_b128 v[20:23], v15 offset:48
	ds_read_b128 v[24:27], v15 offset:8224
	ds_read_b128 v[28:31], v15 offset:8240
	ds_read_b128 v[32:35], v15 offset:16416
	ds_read_b128 v[36:39], v15 offset:16432
	s_waitcnt lgkmcnt(0)
	v_mov_b32_e32 v56, v16
	v_mov_b32_e32 v57, v24
	v_mov_b32_e32 v24, v17
	v_mov_b32_e32 v16, v18
	v_mov_b32_e32 v17, v26
	v_mov_b32_e32 v26, v19
	v_mov_b32_e32 v18, v20
	v_mov_b32_e32 v19, v28
	v_mov_b32_e32 v28, v21
	v_mov_b32_e32 v20, v22
	v_mov_b32_e32 v21, v30
	v_mov_b32_e32 v30, v23
	s_waitcnt vmcnt(23)
	v_pk_fma_f32 v[12:13], v[80:81], v[56:57], v[12:13] op_sel_hi:[0,1,1]
	v_fmac_f32_e32 v14, v80, v32
	s_waitcnt vmcnt(22)
	v_pk_fma_f32 v[12:13], v[82:83], v[24:25], v[12:13] op_sel_hi:[0,1,1]
	v_fmac_f32_e32 v14, v82, v33
	s_waitcnt vmcnt(21)
; __device__ void phase_a(const Params& p, unsigned char* lds) {
;     ...
;         for (int k = kg * 256; k < kg * 256 + 256; ++k) { const float wv = w[(size_t)k * 6144]; a0 += sf[k] * wv; a1 += sf[2048 + k] * wv; a2 += sf[4096 + k] * wv; }
;         float* red = sf + 6144;
;         red[(kg * 3 + 0) * 64 + (tid & 63)] = a0; red[(kg * 3 + 1) * 64 + (tid & 63)] = a1; red[(kg * 3 + 2) * 64 + (tid & 63)] = a2;
;         __syncthreads();
;         if (tid < 192) { const int r = tid >> 6, cc = tid & 63; float s = 0.f;
; #pragma unroll
;             for (int g = 0; g < 8; ++g) s += red[(g * 3 + r) * 64 + cc];
;             const int col2 = cb * 64 + cc; p.MOD[(size_t)(l * 3 + r) * 6144 + col2] = s + p.b_ada[l * 6144 + col2]; }
	v_pk_fma_f32 v[12:13], v[84:85], v[16:17], v[12:13] op_sel_hi:[0,1,1]
	v_fmac_f32_e32 v14, v84, v34
	s_waitcnt vmcnt(20)
	v_pk_fma_f32 v[12:13], v[86:87], v[26:27], v[12:13] op_sel_hi:[0,1,1]
	v_fmac_f32_e32 v14, v86, v35
	s_waitcnt vmcnt(19)
	v_pk_fma_f32 v[12:13], v[88:89], v[18:19], v[12:13] op_sel_hi:[0,1,1]
	v_fmac_f32_e32 v14, v88, v36
	s_waitcnt vmcnt(18)
	v_pk_fma_f32 v[12:13], v[90:91], v[28:29], v[12:13] op_sel_hi:[0,1,1]
	v_fmac_f32_e32 v14, v90, v37
	s_waitcnt vmcnt(17)
	v_pk_fma_f32 v[12:13], v[92:93], v[20:21], v[12:13] op_sel_hi:[0,1,1]
	v_fmac_f32_e32 v14, v92, v38
	s_waitcnt vmcnt(16)
	v_pk_fma_f32 v[12:13], v[94:95], v[30:31], v[12:13] op_sel_hi:[0,1,1]
	v_fmac_f32_e32 v14, v94, v39
	ds_read_b128 v[16:19], v15 offset:64
	ds_read_b128 v[20:23], v15 offset:80
	ds_read_b128 v[24:27], v15 offset:8256
	ds_read_b128 v[28:31], v15 offset:8272
	ds_read_b128 v[32:35], v15 offset:16448
	ds_read_b128 v[36:39], v15 offset:16464
	s_waitcnt lgkmcnt(0)
	v_mov_b32_e32 v56, v16
	v_mov_b32_e32 v57, v24
	v_mov_b32_e32 v24, v17
	v_mov_b32_e32 v16, v18
	v_mov_b32_e32 v17, v26
	v_mov_b32_e32 v26, v19
	v_mov_b32_e32 v18, v20
	v_mov_b32_e32 v19, v28
	v_mov_b32_e32 v28, v21
	v_mov_b32_e32 v20, v22
	v_mov_b32_e32 v21, v30
	v_mov_b32_e32 v30, v23
	s_waitcnt vmcnt(15)
	v_pk_fma_f32 v[12:13], v[96:97], v[56:57], v[12:13] op_sel_hi:[0,1,1]
	v_fmac_f32_e32 v14, v96, v32
	s_waitcnt vmcnt(14)
	v_pk_fma_f32 v[12:13], v[98:99], v[24:25], v[12:13] op_sel_hi:[0,1,1]
	v_fmac_f32_e32 v14, v98, v33
	s_waitcnt vmcnt(13)
	v_pk_fma_f32 v[12:13], v[100:101], v[16:17], v[12:13] op_sel_hi:[0,1,1]
	v_fmac_f32_e32 v14, v100, v34
	s_waitcnt vmcnt(12)
	v_pk_fma_f32 v[12:13], v[102:103], v[26:27], v[12:13] op_sel_hi:[0,1,1]
	v_fmac_f32_e32 v14, v102, v35
	s_waitcnt vmcnt(11)
	v_pk_fma_f32 v[12:13], v[104:105], v[18:19], v[12:13] op_sel_hi:[0,1,1]
	v_fmac_f32_e32 v14, v104, v36
	s_waitcnt vmcnt(10)
	v_pk_fma_f32 v[12:13], v[106:107], v[28:29], v[12:13] op_sel_hi:[0,1,1]
	v_fmac_f32_e32 v14, v106, v37
	s_waitcnt vmcnt(9)
	v_pk_fma_f32 v[12:13], v[108:109], v[20:21], v[12:13] op_sel_hi:[0,1,1]
	v_fmac_f32_e32 v14, v108, v38
	s_waitcnt vmcnt(8)
	v_pk_fma_f32 v[12:13], v[110:111], v[30:31], v[12:13] op_sel_hi:[0,1,1]
	v_fmac_f32_e32 v14, v110, v39
	ds_read_b128 v[16:19], v15 offset:96
	ds_read_b128 v[20:23], v15 offset:112
	ds_read_b128 v[24:27], v15 offset:8288
	ds_read_b128 v[28:31], v15 offset:8304
	ds_read_b128 v[32:35], v15 offset:16480
	ds_read_b128 v[36:39], v15 offset:16496
	s_waitcnt lgkmcnt(0)
	v_mov_b32_e32 v56, v16
	v_mov_b32_e32 v57, v24
	v_mov_b32_e32 v24, v17
	v_mov_b32_e32 v16, v18
	v_mov_b32_e32 v17, v26
	v_mov_b32_e32 v26, v19
	v_mov_b32_e32 v18, v20
	v_mov_b32_e32 v19, v28
	v_mov_b32_e32 v28, v21
	v_mov_b32_e32 v20, v22
	v_mov_b32_e32 v21, v30
	v_mov_b32_e32 v30, v23
	s_waitcnt vmcnt(7)
	v_pk_fma_f32 v[12:13], v[112:113], v[56:57], v[12:13] op_sel_hi:[0,1,1]
	v_fmac_f32_e32 v14, v112, v32
	s_waitcnt vmcnt(6)
	v_pk_fma_f32 v[12:13], v[114:115], v[24:25], v[12:13] op_sel_hi:[0,1,1]
	v_fmac_f32_e32 v14, v114, v33
	s_waitcnt vmcnt(5)
	v_pk_fma_f32 v[12:13], v[116:117], v[16:17], v[12:13] op_sel_hi:[0,1,1]
	v_fmac_f32_e32 v14, v116, v34
	s_waitcnt vmcnt(4)
	v_pk_fma_f32 v[12:13], v[118:119], v[26:27], v[12:13] op_sel_hi:[0,1,1]
	v_fmac_f32_e32 v14, v118, v35
	s_waitcnt vmcnt(3)
	v_pk_fma_f32 v[12:13], v[120:121], v[18:19], v[12:13] op_sel_hi:[0,1,1]
	v_fmac_f32_e32 v14, v120, v36
	s_waitcnt vmcnt(2)
	v_pk_fma_f32 v[12:13], v[122:123], v[28:29], v[12:13] op_sel_hi:[0,1,1]
	v_fmac_f32_e32 v14, v122, v37
	s_waitcnt vmcnt(1)
	v_pk_fma_f32 v[12:13], v[124:125], v[20:21], v[12:13] op_sel_hi:[0,1,1]
	v_fmac_f32_e32 v14, v124, v38
	s_waitcnt vmcnt(0)
	v_pk_fma_f32 v[12:13], v[126:127], v[30:31], v[12:13] op_sel_hi:[0,1,1]
	v_fmac_f32_e32 v14, v126, v39
	v_add_u32_e32 v15, 0x80, v15
	s_cmp_eq_u32 s16, 0x600000
	s_cbranch_scc0 .LBB0_448
	ds_write2st64_b32 v4, v12, v13 offset0:96 offset1:97
	ds_write_b32 v4, v14 offset:25088
	s_waitcnt lgkmcnt(0)
	s_barrier
	s_and_saveexec_b64 s[6:7], vcc
	s_cbranch_execz .LBB0_446
	s_mul_i32 s16, s18, 0x1800
	v_add_u32_e32 v10, s16, v8
	v_ashrrev_i32_e32 v11, 31, v10
	v_lshl_add_u64 v[10:11], v[10:11], 2, s[12:13]
	global_load_dword v22, v[10:11], off
	v_add_u32_e32 v20, v2, v3
	ds_read2st64_b32 v[14:15], v20 offset0:96 offset1:99
	ds_read2st64_b32 v[16:17], v20 offset0:102 offset1:105
	ds_read2st64_b32 v[18:19], v20 offset0:108 offset1:111
	ds_read2st64_b32 v[20:21], v20 offset0:114 offset1:117
	v_mad_u64_u32 v[10:11], s[16:17], s18, 3, v[0:1]
	v_mov_b64_e32 v[12:13], s[14:15]
	v_mad_i64_i32 v[10:11], s[16:17], v10, s65, v[12:13]
	s_waitcnt lgkmcnt(3)
	v_add_f32_e32 v12, 0, v14
	v_add_f32_e32 v12, v12, v15
	s_waitcnt lgkmcnt(2)
	v_add_f32_e32 v12, v12, v16
	v_add_f32_e32 v12, v12, v17
	s_waitcnt lgkmcnt(1)
	v_add_f32_e32 v12, v12, v18
	v_add_f32_e32 v12, v12, v19
	s_waitcnt lgkmcnt(0)
	v_add_f32_e32 v12, v12, v20
	v_add_f32_e32 v12, v12, v21
	v_lshl_add_u64 v[8:9], v[8:9], 2, v[10:11]
	s_waitcnt vmcnt(0)
	v_add_f32_e32 v12, v12, v22
	global_store_dword v[8:9], v12, off
	s_branch .LBB0_446
